# all validated edits combined (timing 1 of 3): no-permlane P path, V in flight over the barrier, k-step-major P.V, static priority, prologue DMA hoist, epilogue load hoist, serpentine GEMM order, stati
# speedup vs baseline: 1.0102x; 1.0055x over previous
.Lmla_loop:
	ds_read_b128 v[214:217], v166 offset:32768
	ds_read_b128 v[218:221], v166 offset:40960
	ds_read_b128 v[222:225], v167 offset:32768
	ds_read_b128 v[226:229], v167 offset:40960
	ds_read_b128 v[230:233], v168 offset:32768
	ds_read_b128 v[234:237], v168 offset:40960
	v_lshl_add_u32 v183, s52, 14, v192
	s_mov_b32 m0, s45
	s_lshl_b32 s8, s49, 14
	global_load_lds_dwordx4 v178, s[98:99]
	v_exp_f32_e32 v144, v144
	v_add_f32_e32 v243, v128, v129
	v_add_f32_e32 v244, v130, v131
	v_exp_f32_e32 v145, v145
	s_waitcnt lgkmcnt(4)
	v_mfma_f32_32x32x16_bf16 v[64:79], v[214:217], v[124:127], v[198:213]
	s_mov_b32 m0, s77
	s_add_i32 s12, s8, s44
	global_load_lds_dwordx4 v179, s[98:99]
	v_cvt_pk_bf16_f32 v128, v128, v129
	v_add_f32_e32 v243, v132, v243
	v_exp_f32_e32 v146, v146
	v_mfma_f32_32x32x16_bf16 v[80:95], v[218:221], v[124:127], v[198:213]
	ds_read_b128 v[214:217], v169 offset:32768
	ds_read_b128 v[218:221], v169 offset:40960
	v_cvt_pk_bf16_f32 v129, v130, v131
	v_add_f32_e32 v244, v133, v244
	v_exp_f32_e32 v147, v147
	s_waitcnt lgkmcnt(4)
	v_mfma_f32_32x32x16_bf16 v[64:79], v[222:225], v[120:123], v[64:79]
	s_mov_b32 m0, s9
	s_nop 0
	global_load_lds_dwordx4 v182, s[100:101]
	s_add_u32 s100, s100, 0x2000
	s_addc_u32 s101, s101, 0
	v_add_f32_e32 v243, v134, v243
	v_cvt_pk_bf16_f32 v130, v132, v133
	v_exp_f32_e32 v148, v148
	v_mfma_f32_32x32x16_bf16 v[80:95], v[226:229], v[120:123], v[80:95]
	ds_read_b128 v[222:225], v170 offset:32768
	ds_read_b128 v[226:229], v170 offset:40960
	v_add_f32_e32 v244, v135, v244
	v_exp_f32_e32 v149, v149
	v_add_f32_e32 v243, v136, v243
	s_waitcnt lgkmcnt(4)
	v_mfma_f32_32x32x16_bf16 v[64:79], v[230:233], v[116:119], v[64:79]
	s_mov_b32 m0, s12
	s_add_i32 s12, s8, s47
	global_load_lds_dwordx4 v180, s[98:99]
	v_cvt_pk_bf16_f32 v131, v134, v135
	v_exp_f32_e32 v150, v150
	v_add_f32_e32 v244, v137, v244
	v_mfma_f32_32x32x16_bf16 v[80:95], v[234:237], v[116:119], v[80:95]
	ds_read_b128 v[230:233], v171 offset:32768
	ds_read_b128 v[234:237], v171 offset:40960
	v_exp_f32_e32 v151, v151
	v_add_f32_e32 v243, v138, v243
	v_cvt_pk_bf16_f32 v132, v136, v137
	s_waitcnt lgkmcnt(4)
	v_mfma_f32_32x32x16_bf16 v[64:79], v[214:217], v[112:115], v[64:79]
	s_mov_b32 m0, s12
	s_nop 0
	global_load_lds_dwordx4 v181, s[98:99]
	s_add_u32 s98, s98, 0x40000
	s_addc_u32 s99, s99, 0
	v_exp_f32_e32 v152, v152
	v_add_f32_e32 v244, v139, v244
	v_exp_f32_e32 v153, v153
	v_mfma_f32_32x32x16_bf16 v[80:95], v[218:221], v[112:115], v[80:95]
	ds_read_b128 v[214:217], v172 offset:32768
	ds_read_b128 v[218:221], v172 offset:40960
	v_add_f32_e32 v243, v140, v243
	v_cvt_pk_bf16_f32 v133, v138, v139
	v_add_f32_e32 v244, v141, v244
	v_exp_f32_e32 v154, v154
	s_waitcnt lgkmcnt(4)
	v_mfma_f32_32x32x16_bf16 v[64:79], v[222:225], v[108:111], v[64:79]
	v_add_f32_e32 v243, v142, v243
	v_exp_f32_e32 v155, v155
	v_cvt_pk_bf16_f32 v134, v140, v141
	v_mfma_f32_32x32x16_bf16 v[80:95], v[226:229], v[108:111], v[80:95]
	ds_read_b128 v[222:225], v173 offset:32768
	ds_read_b128 v[226:229], v173 offset:40960
	v_add_f32_e32 v244, v143, v244
	v_exp_f32_e32 v156, v156
	v_add_f32_e32 v243, v144, v243
	s_waitcnt lgkmcnt(4)
	v_mfma_f32_32x32x16_bf16 v[64:79], v[230:233], v[104:107], v[64:79]
	v_cvt_pk_bf16_f32 v135, v142, v143
	v_exp_f32_e32 v157, v157
	v_add_f32_e32 v244, v145, v244
	v_mfma_f32_32x32x16_bf16 v[80:95], v[234:237], v[104:107], v[80:95]
	ds_read_b128 v[230:233], v174 offset:8192
	ds_read_b128 v[234:237], v174 offset:12288
	v_exp_f32_e32 v158, v158
	v_add_f32_e32 v243, v146, v243
	v_cvt_pk_bf16_f32 v144, v144, v145
	s_waitcnt lgkmcnt(4)
	v_mfma_f32_32x32x16_bf16 v[64:79], v[214:217], v[100:103], v[64:79]
	v_exp_f32_e32 v159, v159
	v_add_f32_e32 v244, v147, v244
	v_add_f32_e32 v243, v148, v243
	v_mfma_f32_32x32x16_bf16 v[80:95], v[218:221], v[100:103], v[80:95]
	ds_read_b128 v[214:217], v175 offset:8192
	ds_read_b128 v[218:221], v175 offset:12288
	v_cvt_pk_bf16_f32 v145, v146, v147
	v_add_f32_e32 v244, v149, v244
	v_add_f32_e32 v243, v150, v243
	v_cvt_pk_bf16_f32 v146, v148, v149
	s_waitcnt lgkmcnt(4)
	v_mfma_f32_32x32x16_bf16 v[64:79], v[222:225], v[96:99], v[64:79]
	v_add_f32_e32 v244, v151, v244
	v_add_f32_e32 v243, v152, v243
	v_cvt_pk_bf16_f32 v147, v150, v151
	v_add_f32_e32 v244, v153, v244
	v_mfma_f32_32x32x16_bf16 v[80:95], v[226:229], v[96:99], v[80:95]
	ds_read_b128 v[222:225], v176 offset:8192
	ds_read_b128 v[226:229], v176 offset:12288
	v_add_f32_e32 v243, v154, v243
	v_cvt_pk_bf16_f32 v148, v152, v153
	v_add_f32_e32 v244, v155, v244
	v_add_f32_e32 v243, v156, v243
	s_waitcnt lgkmcnt(4)
	v_mfma_f32_32x32x16_bf16 v[64:79], v[230:233], v[246:249], v[64:79]
	v_cvt_pk_bf16_f32 v149, v154, v155
	v_add_f32_e32 v244, v157, v244
	v_add_f32_e32 v243, v158, v243
	v_cvt_pk_bf16_f32 v150, v156, v157
	v_mfma_f32_32x32x16_bf16 v[80:95], v[234:237], v[246:249], v[80:95]
	ds_read_b128 v[230:233], v177 offset:8192
	ds_read_b128 v[234:237], v177 offset:12288
	v_add_f32_e32 v244, v159, v244
	v_cvt_pk_bf16_f32 v151, v158, v159
	v_add_f32_e32 v243, v243, v244
	v_mov_b32_e32 v244, v243
	s_waitcnt lgkmcnt(4)
	v_mfma_f32_32x32x16_bf16 v[64:79], v[214:217], v[250:253], v[64:79]
	v_permlane32_swap_b32_e32 v243, v244
	v_add_f32_e32 v243, v243, v244
	v_fma_f32 v163, v163, v242, v243
	v_mfma_f32_32x32x16_bf16 v[80:95], v[218:221], v[250:253], v[80:95]
	ds_read_b64_tr_b16 v[214:215], v183
	ds_read_b64_tr_b16 v[216:217], v183 offset:256
	ds_read_b64_tr_b16 v[218:219], v183 offset:512
	ds_read_b64_tr_b16 v[220:221], v183 offset:768
	s_waitcnt lgkmcnt(6)
	v_mfma_f32_32x32x16_bf16 v[64:79], v[222:225], v[186:189], v[64:79]
	v_mfma_f32_32x32x16_bf16 v[80:95], v[226:229], v[186:189], v[80:95]
	ds_read_b64_tr_b16 v[222:223], v183 offset:1024
	ds_read_b64_tr_b16 v[224:225], v183 offset:1280
	ds_read_b64_tr_b16 v[226:227], v183 offset:1536
	ds_read_b64_tr_b16 v[228:229], v183 offset:1792
	s_waitcnt lgkmcnt(8)
	v_mfma_f32_32x32x16_bf16 v[64:79], v[230:233], v[238:241], v[64:79]
	v_mfma_f32_32x32x16_bf16 v[80:95], v[234:237], v[238:241], v[80:95]
	s_waitcnt lgkmcnt(6)
	v_mfma_f32_32x32x16_bf16 v[0:15], v[128:131], v[214:217], v[0:15]
	ds_read_b64_tr_b16 v[136:137], v183 offset:4096
	ds_read_b64_tr_b16 v[138:139], v183 offset:4352
	s_waitcnt lgkmcnt(6)
	v_mfma_f32_32x32x16_bf16 v[48:63], v[128:131], v[218:221], v[48:63]
	ds_read_b64_tr_b16 v[140:141], v183 offset:4608
	ds_read_b64_tr_b16 v[142:143], v183 offset:4864
	s_waitcnt lgkmcnt(6)
	v_mfma_f32_32x32x16_bf16 v[32:47], v[128:131], v[222:225], v[32:47]
	ds_read_b64_tr_b16 v[152:153], v183 offset:5120
	ds_read_b64_tr_b16 v[154:155], v183 offset:5376
	v_max3_f32 v196, v64, v65, v66
	v_max3_f32 v197, v80, v81, v82
	v_max3_f32 v196, v196, v67, v68
	v_max3_f32 v197, v197, v83, v84
	v_max3_f32 v196, v196, v69, v70
	v_max3_f32 v197, v197, v85, v86
	s_waitcnt lgkmcnt(6)
	v_mfma_f32_32x32x16_bf16 v[16:31], v[128:131], v[226:229], v[16:31]
	ds_read_b64_tr_b16 v[156:157], v183 offset:5632
	ds_read_b64_tr_b16 v[158:159], v183 offset:5888
	v_max3_f32 v196, v196, v71, v72
	v_max3_f32 v197, v197, v87, v88
	v_max3_f32 v196, v196, v73, v74
	v_max3_f32 v197, v197, v89, v90
	v_max3_f32 v196, v196, v75, v76
	v_max3_f32 v197, v197, v91, v92
	s_waitcnt lgkmcnt(6)
	v_mfma_f32_32x32x16_bf16 v[0:15], v[132:135], v[136:139], v[0:15]
	ds_read_b64_tr_b16 v[214:215], v183 offset:8192
	ds_read_b64_tr_b16 v[216:217], v183 offset:8448
	v_max3_f32 v196, v196, v77, v78
	v_max3_f32 v197, v197, v93, v94
	v_max_f32_e32 v196, v196, v79
	v_max_f32_e32 v197, v197, v95
	v_max_f32_e32 v196, v196, v197
	v_mov_b32_e32 v197, v196
	s_waitcnt lgkmcnt(6)
	v_mfma_f32_32x32x16_bf16 v[48:63], v[132:135], v[140:143], v[48:63]
	ds_read_b64_tr_b16 v[218:219], v183 offset:8704
	ds_read_b64_tr_b16 v[220:221], v183 offset:8960
	v_permlane32_swap_b32_e32 v196, v197
	v_max_f32_e32 v196, v196, v197
	v_cmp_ge_f32_e32 vcc, s97, v196
	s_cmp_eq_u64 vcc, exec
	s_cselect_b64 s[42:43], -1, 0
	v_mov_b32_e32 v193, 1.0
	s_mov_b64 s[12:13], 0
	s_cmp_lg_u64 s[42:43], 0
	s_cbranch_scc1 .Lmla_ok_A
	v_max_f32_e32 v197, 0, v196
	v_exp_f32_e64 v193, -v197
	v_sub_f32_e32 v64, v64, v197
	v_sub_f32_e32 v65, v65, v197
	v_sub_f32_e32 v66, v66, v197
	v_sub_f32_e32 v67, v67, v197
	v_sub_f32_e32 v68, v68, v197
	v_sub_f32_e32 v69, v69, v197
	v_sub_f32_e32 v70, v70, v197
	v_sub_f32_e32 v71, v71, v197
	v_sub_f32_e32 v72, v72, v197
	v_sub_f32_e32 v73, v73, v197
	v_sub_f32_e32 v74, v74, v197
	v_sub_f32_e32 v75, v75, v197
	v_sub_f32_e32 v76, v76, v197
	v_sub_f32_e32 v77, v77, v197
	v_sub_f32_e32 v78, v78, v197
	v_sub_f32_e32 v79, v79, v197
	v_sub_f32_e32 v80, v80, v197
	v_sub_f32_e32 v81, v81, v197
	v_sub_f32_e32 v82, v82, v197
	v_sub_f32_e32 v83, v83, v197
	v_sub_f32_e32 v84, v84, v197
	v_sub_f32_e32 v85, v85, v197
	v_sub_f32_e32 v86, v86, v197
	v_sub_f32_e32 v87, v87, v197
	v_sub_f32_e32 v88, v88, v197
	v_sub_f32_e32 v89, v89, v197
	v_sub_f32_e32 v90, v90, v197
	v_sub_f32_e32 v91, v91, v197
	v_sub_f32_e32 v92, v92, v197
	v_sub_f32_e32 v93, v93, v197
	v_sub_f32_e32 v94, v94, v197
	v_sub_f32_e32 v95, v95, v197
	v_sub_f32_e32 v198, v198, v197
	v_sub_f32_e32 v199, v199, v197
	v_sub_f32_e32 v200, v200, v197
	v_sub_f32_e32 v201, v201, v197
	v_sub_f32_e32 v202, v202, v197
	v_sub_f32_e32 v203, v203, v197
	v_sub_f32_e32 v204, v204, v197
	v_sub_f32_e32 v205, v205, v197
	v_sub_f32_e32 v206, v206, v197
	v_sub_f32_e32 v207, v207, v197
	v_sub_f32_e32 v208, v208, v197
	v_sub_f32_e32 v209, v209, v197
	v_sub_f32_e32 v210, v210, v197
	v_sub_f32_e32 v211, v211, v197
	v_sub_f32_e32 v212, v212, v197
	v_sub_f32_e32 v213, v213, v197
	v_cmp_gt_f32_e64 s[12:13], 1.0, v193
.Lmla_ok_A:
	s_waitcnt lgkmcnt(6)
	v_mfma_f32_32x32x16_bf16 v[32:47], v[132:135], v[152:155], v[32:47]
	ds_read_b64_tr_b16 v[222:223], v183 offset:9216
	ds_read_b64_tr_b16 v[224:225], v183 offset:9472
	v_exp_f32_e32 v64, v64
	v_exp_f32_e32 v65, v65
	v_exp_f32_e32 v66, v66
	s_waitcnt lgkmcnt(6)
	v_mfma_f32_32x32x16_bf16 v[16:31], v[132:135], v[156:159], v[16:31]
	ds_read_b64_tr_b16 v[226:227], v183 offset:9728
	ds_read_b64_tr_b16 v[228:229], v183 offset:9984
	v_exp_f32_e32 v67, v67
	v_exp_f32_e32 v68, v68
	v_exp_f32_e32 v69, v69
	s_waitcnt lgkmcnt(6)
	v_mfma_f32_32x32x16_bf16 v[0:15], v[144:147], v[214:217], v[0:15]
	ds_read_b64_tr_b16 v[136:137], v183 offset:12288
	ds_read_b64_tr_b16 v[138:139], v183 offset:12544
	v_exp_f32_e32 v70, v70
	v_exp_f32_e32 v71, v71
	v_exp_f32_e32 v72, v72
	s_waitcnt lgkmcnt(6)
	v_mfma_f32_32x32x16_bf16 v[48:63], v[144:147], v[218:221], v[48:63]
	ds_read_b64_tr_b16 v[140:141], v183 offset:12800
	ds_read_b64_tr_b16 v[142:143], v183 offset:13056
	v_exp_f32_e32 v73, v73
	v_exp_f32_e32 v74, v74
	v_exp_f32_e32 v75, v75
	s_waitcnt lgkmcnt(6)
	v_mfma_f32_32x32x16_bf16 v[32:47], v[144:147], v[222:225], v[32:47]
	ds_read_b64_tr_b16 v[152:153], v183 offset:13312
	ds_read_b64_tr_b16 v[154:155], v183 offset:13568
	v_exp_f32_e32 v76, v76
	v_exp_f32_e32 v77, v77
	v_exp_f32_e32 v78, v78
	s_waitcnt lgkmcnt(6)
	v_mfma_f32_32x32x16_bf16 v[16:31], v[144:147], v[226:229], v[16:31]
	ds_read_b64_tr_b16 v[156:157], v183 offset:13824
	ds_read_b64_tr_b16 v[158:159], v183 offset:14080
	v_exp_f32_e32 v79, v79
	s_waitcnt lgkmcnt(6)
	v_mfma_f32_32x32x16_bf16 v[0:15], v[148:151], v[136:139], v[0:15]
	s_waitcnt lgkmcnt(4)
	v_mfma_f32_32x32x16_bf16 v[48:63], v[148:151], v[140:143], v[48:63]
	s_waitcnt lgkmcnt(2)
	v_mfma_f32_32x32x16_bf16 v[32:47], v[148:151], v[152:155], v[32:47]
	s_waitcnt lgkmcnt(0)
	v_mfma_f32_32x32x16_bf16 v[16:31], v[148:151], v[156:159], v[16:31]
	s_cmp_lg_u64 s[12:13], 0
	s_cbranch_scc0 .Lmla_nors_A
	s_and_saveexec_b64 s[20:21], s[40:41]
	ds_write_b32 v162, v193 offset:128
	s_or_b64 exec, exec, s[20:21]
	s_waitcnt lgkmcnt(0)
	v_add_u32_e32 v245, s37, v184
	ds_read_b128 v[214:217], v245 offset:128
	ds_read_b128 v[218:221], v245 offset:160
	ds_read_b128 v[222:225], v245 offset:192
	ds_read_b128 v[226:229], v245 offset:224
	s_waitcnt lgkmcnt(0)
	v_pk_mul_f32 v[0:1], v[0:1], v[214:215]
	v_pk_mul_f32 v[2:3], v[2:3], v[216:217]
	v_pk_mul_f32 v[4:5], v[4:5], v[218:219]
	v_pk_mul_f32 v[6:7], v[6:7], v[220:221]
	v_pk_mul_f32 v[8:9], v[8:9], v[222:223]
	v_pk_mul_f32 v[10:11], v[10:11], v[224:225]
	v_pk_mul_f32 v[12:13], v[12:13], v[226:227]
	v_pk_mul_f32 v[14:15], v[14:15], v[228:229]
	v_pk_mul_f32 v[48:49], v[48:49], v[214:215]
	v_pk_mul_f32 v[50:51], v[50:51], v[216:217]
	v_pk_mul_f32 v[52:53], v[52:53], v[218:219]
	v_pk_mul_f32 v[54:55], v[54:55], v[220:221]
	v_pk_mul_f32 v[56:57], v[56:57], v[222:223]
	v_pk_mul_f32 v[58:59], v[58:59], v[224:225]
	v_pk_mul_f32 v[60:61], v[60:61], v[226:227]
	v_pk_mul_f32 v[62:63], v[62:63], v[228:229]
	v_pk_mul_f32 v[32:33], v[32:33], v[214:215]
	v_pk_mul_f32 v[34:35], v[34:35], v[216:217]
	v_pk_mul_f32 v[36:37], v[36:37], v[218:219]
	v_pk_mul_f32 v[38:39], v[38:39], v[220:221]
	v_pk_mul_f32 v[40:41], v[40:41], v[222:223]
	v_pk_mul_f32 v[42:43], v[42:43], v[224:225]
	v_pk_mul_f32 v[44:45], v[44:45], v[226:227]
	v_pk_mul_f32 v[46:47], v[46:47], v[228:229]
	v_pk_mul_f32 v[16:17], v[16:17], v[214:215]
	v_pk_mul_f32 v[18:19], v[18:19], v[216:217]
	v_pk_mul_f32 v[20:21], v[20:21], v[218:219]
	v_pk_mul_f32 v[22:23], v[22:23], v[220:221]
	v_pk_mul_f32 v[24:25], v[24:25], v[222:223]
	v_pk_mul_f32 v[26:27], v[26:27], v[224:225]
	v_pk_mul_f32 v[28:29], v[28:29], v[226:227]
	v_pk_mul_f32 v[30:31], v[30:31], v[228:229]
.Lmla_nors_A:
	s_add_i32 s8, s52, 1
	s_cmp_lg_u32 s52, 2
	s_cselect_b32 s14, s8, 0
	s_add_i32 s8, s49, 1
	s_cmp_lg_u32 s49, 2
	s_cselect_b32 s15, s8, 0
	s_waitcnt vmcnt(2) lgkmcnt(0)
	s_barrier
	ds_read_b128 v[214:217], v166 offset:16384
	ds_read_b128 v[218:221], v166 offset:24576
	ds_read_b128 v[222:225], v167 offset:16384
	ds_read_b128 v[226:229], v167 offset:24576
	ds_read_b128 v[230:233], v168 offset:16384
	ds_read_b128 v[234:237], v168 offset:24576
	v_lshl_add_u32 v183, s14, 14, v192
	s_mov_b32 m0, s93
	s_lshl_b32 s8, s15, 14
	global_load_lds_dwordx4 v178, s[98:99]
	v_exp_f32_e32 v80, v80
	v_add_f32_e32 v243, v64, v65
	v_add_f32_e32 v244, v66, v67
	v_exp_f32_e32 v81, v81
	s_waitcnt lgkmcnt(4)
	v_mfma_f32_32x32x16_bf16 v[128:143], v[214:217], v[124:127], v[198:213]
	s_mov_b32 m0, s50
	s_add_i32 s12, s8, s44
	global_load_lds_dwordx4 v179, s[98:99]
	v_cvt_pk_bf16_f32 v64, v64, v65
	v_add_f32_e32 v243, v68, v243
	v_exp_f32_e32 v82, v82
	v_mfma_f32_32x32x16_bf16 v[144:159], v[218:221], v[124:127], v[198:213]
	ds_read_b128 v[214:217], v169 offset:16384
	ds_read_b128 v[218:221], v169 offset:24576
	v_cvt_pk_bf16_f32 v65, v66, v67
	v_add_f32_e32 v244, v69, v244
	v_exp_f32_e32 v83, v83
	s_waitcnt lgkmcnt(4)
	v_mfma_f32_32x32x16_bf16 v[128:143], v[222:225], v[120:123], v[128:143]
	s_mov_b32 m0, s51
	s_nop 0
	global_load_lds_dwordx4 v182, s[100:101]
	s_add_u32 s100, s100, 0x2000
	s_addc_u32 s101, s101, 0
	v_add_f32_e32 v243, v70, v243
	v_cvt_pk_bf16_f32 v66, v68, v69
	v_exp_f32_e32 v84, v84
	v_mfma_f32_32x32x16_bf16 v[144:159], v[226:229], v[120:123], v[144:159]
	ds_read_b128 v[222:225], v170 offset:16384
	ds_read_b128 v[226:229], v170 offset:24576
	v_add_f32_e32 v244, v71, v244
	v_exp_f32_e32 v85, v85
	v_add_f32_e32 v243, v72, v243
	s_waitcnt lgkmcnt(4)
	v_mfma_f32_32x32x16_bf16 v[128:143], v[230:233], v[116:119], v[128:143]
	s_mov_b32 m0, s12
	s_add_i32 s12, s8, s47
	global_load_lds_dwordx4 v180, s[98:99]
	v_cvt_pk_bf16_f32 v67, v70, v71
	v_exp_f32_e32 v86, v86
	v_add_f32_e32 v244, v73, v244
	v_mfma_f32_32x32x16_bf16 v[144:159], v[234:237], v[116:119], v[144:159]
	ds_read_b128 v[230:233], v171 offset:16384
	ds_read_b128 v[234:237], v171 offset:24576
	v_exp_f32_e32 v87, v87
	v_add_f32_e32 v243, v74, v243
	v_cvt_pk_bf16_f32 v68, v72, v73
	s_waitcnt lgkmcnt(4)
	v_mfma_f32_32x32x16_bf16 v[128:143], v[214:217], v[112:115], v[128:143]
	s_mov_b32 m0, s12
	s_nop 0
	global_load_lds_dwordx4 v181, s[98:99]
	s_add_u32 s98, s98, 0x40000
	s_addc_u32 s99, s99, 0
	v_exp_f32_e32 v88, v88
	v_add_f32_e32 v244, v75, v244
	v_exp_f32_e32 v89, v89
	v_mfma_f32_32x32x16_bf16 v[144:159], v[218:221], v[112:115], v[144:159]
	ds_read_b128 v[214:217], v172 offset:16384
	ds_read_b128 v[218:221], v172 offset:24576
	v_add_f32_e32 v243, v76, v243
	v_cvt_pk_bf16_f32 v69, v74, v75
	v_add_f32_e32 v244, v77, v244
	v_exp_f32_e32 v90, v90
	s_waitcnt lgkmcnt(4)
	v_mfma_f32_32x32x16_bf16 v[128:143], v[222:225], v[108:111], v[128:143]
	v_add_f32_e32 v243, v78, v243
	v_exp_f32_e32 v91, v91
	v_cvt_pk_bf16_f32 v70, v76, v77
	v_mfma_f32_32x32x16_bf16 v[144:159], v[226:229], v[108:111], v[144:159]
	ds_read_b128 v[222:225], v173 offset:16384
	ds_read_b128 v[226:229], v173 offset:24576
	v_add_f32_e32 v244, v79, v244
	v_exp_f32_e32 v92, v92
	v_add_f32_e32 v243, v80, v243
	s_waitcnt lgkmcnt(4)
	v_mfma_f32_32x32x16_bf16 v[128:143], v[230:233], v[104:107], v[128:143]
	v_cvt_pk_bf16_f32 v71, v78, v79
	v_exp_f32_e32 v93, v93
	v_add_f32_e32 v244, v81, v244
	v_mfma_f32_32x32x16_bf16 v[144:159], v[234:237], v[104:107], v[144:159]
	ds_read_b128 v[230:233], v174
	ds_read_b128 v[234:237], v174 offset:4096
	v_exp_f32_e32 v94, v94
	v_add_f32_e32 v243, v82, v243
	v_cvt_pk_bf16_f32 v80, v80, v81
	s_waitcnt lgkmcnt(4)
	v_mfma_f32_32x32x16_bf16 v[128:143], v[214:217], v[100:103], v[128:143]
	v_exp_f32_e32 v95, v95
	v_add_f32_e32 v244, v83, v244
	v_add_f32_e32 v243, v84, v243
	v_mfma_f32_32x32x16_bf16 v[144:159], v[218:221], v[100:103], v[144:159]
	ds_read_b128 v[214:217], v175
	ds_read_b128 v[218:221], v175 offset:4096
	v_cvt_pk_bf16_f32 v81, v82, v83
	v_add_f32_e32 v244, v85, v244
	v_add_f32_e32 v243, v86, v243
	v_cvt_pk_bf16_f32 v82, v84, v85
	s_waitcnt lgkmcnt(4)
	v_mfma_f32_32x32x16_bf16 v[128:143], v[222:225], v[96:99], v[128:143]
	v_add_f32_e32 v244, v87, v244
	v_add_f32_e32 v243, v88, v243
	v_cvt_pk_bf16_f32 v83, v86, v87
	v_add_f32_e32 v244, v89, v244
	v_mfma_f32_32x32x16_bf16 v[144:159], v[226:229], v[96:99], v[144:159]
	ds_read_b128 v[222:225], v176
	ds_read_b128 v[226:229], v176 offset:4096
	v_add_f32_e32 v243, v90, v243
	v_cvt_pk_bf16_f32 v84, v88, v89
	v_add_f32_e32 v244, v91, v244
	v_add_f32_e32 v243, v92, v243
	s_waitcnt lgkmcnt(4)
	v_mfma_f32_32x32x16_bf16 v[128:143], v[230:233], v[246:249], v[128:143]
	v_cvt_pk_bf16_f32 v85, v90, v91
	v_add_f32_e32 v244, v93, v244
	v_add_f32_e32 v243, v94, v243
	v_cvt_pk_bf16_f32 v86, v92, v93
	v_mfma_f32_32x32x16_bf16 v[144:159], v[234:237], v[246:249], v[144:159]
	ds_read_b128 v[230:233], v177
	ds_read_b128 v[234:237], v177 offset:4096
	v_add_f32_e32 v244, v95, v244
	v_cvt_pk_bf16_f32 v87, v94, v95
	v_add_f32_e32 v243, v243, v244
	v_mov_b32_e32 v244, v243
	s_waitcnt lgkmcnt(4)
	v_mfma_f32_32x32x16_bf16 v[128:143], v[214:217], v[250:253], v[128:143]
	v_permlane32_swap_b32_e32 v243, v244
	v_add_f32_e32 v243, v243, v244
	v_fma_f32 v163, v163, v193, v243
	v_mfma_f32_32x32x16_bf16 v[144:159], v[218:221], v[250:253], v[144:159]
	ds_read_b64_tr_b16 v[214:215], v183
	ds_read_b64_tr_b16 v[216:217], v183 offset:256
	ds_read_b64_tr_b16 v[218:219], v183 offset:512
	ds_read_b64_tr_b16 v[220:221], v183 offset:768
	s_waitcnt lgkmcnt(6)
	v_mfma_f32_32x32x16_bf16 v[128:143], v[222:225], v[186:189], v[128:143]
	v_mfma_f32_32x32x16_bf16 v[144:159], v[226:229], v[186:189], v[144:159]
	ds_read_b64_tr_b16 v[222:223], v183 offset:1024
	ds_read_b64_tr_b16 v[224:225], v183 offset:1280
	ds_read_b64_tr_b16 v[226:227], v183 offset:1536
	ds_read_b64_tr_b16 v[228:229], v183 offset:1792
	s_waitcnt lgkmcnt(8)
	v_mfma_f32_32x32x16_bf16 v[128:143], v[230:233], v[238:241], v[128:143]
	v_mfma_f32_32x32x16_bf16 v[144:159], v[234:237], v[238:241], v[144:159]
	s_waitcnt lgkmcnt(6)
	v_mfma_f32_32x32x16_bf16 v[0:15], v[64:67], v[214:217], v[0:15]
	ds_read_b64_tr_b16 v[72:73], v183 offset:4096
	ds_read_b64_tr_b16 v[74:75], v183 offset:4352
	s_waitcnt lgkmcnt(6)
	v_mfma_f32_32x32x16_bf16 v[48:63], v[64:67], v[218:221], v[48:63]
	ds_read_b64_tr_b16 v[76:77], v183 offset:4608
	ds_read_b64_tr_b16 v[78:79], v183 offset:4864
	s_waitcnt lgkmcnt(6)
	v_mfma_f32_32x32x16_bf16 v[32:47], v[64:67], v[222:225], v[32:47]
	ds_read_b64_tr_b16 v[88:89], v183 offset:5120
	ds_read_b64_tr_b16 v[90:91], v183 offset:5376
	v_max3_f32 v196, v128, v129, v130
	v_max3_f32 v197, v144, v145, v146
	v_max3_f32 v196, v196, v131, v132
	v_max3_f32 v197, v197, v147, v148
	v_max3_f32 v196, v196, v133, v134
	v_max3_f32 v197, v197, v149, v150
	s_waitcnt lgkmcnt(6)
	v_mfma_f32_32x32x16_bf16 v[16:31], v[64:67], v[226:229], v[16:31]
	ds_read_b64_tr_b16 v[92:93], v183 offset:5632
	ds_read_b64_tr_b16 v[94:95], v183 offset:5888
	v_max3_f32 v196, v196, v135, v136
	v_max3_f32 v197, v197, v151, v152
	v_max3_f32 v196, v196, v137, v138
	v_max3_f32 v197, v197, v153, v154
	v_max3_f32 v196, v196, v139, v140
	v_max3_f32 v197, v197, v155, v156
	s_waitcnt lgkmcnt(6)
	v_mfma_f32_32x32x16_bf16 v[0:15], v[68:71], v[72:75], v[0:15]
	ds_read_b64_tr_b16 v[214:215], v183 offset:8192
	ds_read_b64_tr_b16 v[216:217], v183 offset:8448
	v_max3_f32 v196, v196, v141, v142
	v_max3_f32 v197, v197, v157, v158
	v_max_f32_e32 v196, v196, v143
	v_max_f32_e32 v197, v197, v159
	v_max_f32_e32 v196, v196, v197
	v_mov_b32_e32 v197, v196
	s_waitcnt lgkmcnt(6)
	v_mfma_f32_32x32x16_bf16 v[48:63], v[68:71], v[76:79], v[48:63]
	ds_read_b64_tr_b16 v[218:219], v183 offset:8704
	ds_read_b64_tr_b16 v[220:221], v183 offset:8960
	v_permlane32_swap_b32_e32 v196, v197
	v_max_f32_e32 v196, v196, v197
	v_cmp_ge_f32_e32 vcc, s97, v196
	s_cmp_eq_u64 vcc, exec
	s_cselect_b64 s[42:43], -1, 0
	v_mov_b32_e32 v242, 1.0
	s_mov_b64 s[12:13], 0
	s_cmp_lg_u64 s[42:43], 0
	s_cbranch_scc1 .Lmla_ok_B
	v_max_f32_e32 v197, 0, v196
	v_exp_f32_e64 v242, -v197
	v_sub_f32_e32 v128, v128, v197
	v_sub_f32_e32 v129, v129, v197
	v_sub_f32_e32 v130, v130, v197
	v_sub_f32_e32 v131, v131, v197
	v_sub_f32_e32 v132, v132, v197
	v_sub_f32_e32 v133, v133, v197
	v_sub_f32_e32 v134, v134, v197
	v_sub_f32_e32 v135, v135, v197
	v_sub_f32_e32 v136, v136, v197
	v_sub_f32_e32 v137, v137, v197
	v_sub_f32_e32 v138, v138, v197
	v_sub_f32_e32 v139, v139, v197
	v_sub_f32_e32 v140, v140, v197
	v_sub_f32_e32 v141, v141, v197
	v_sub_f32_e32 v142, v142, v197
	v_sub_f32_e32 v143, v143, v197
	v_sub_f32_e32 v144, v144, v197
	v_sub_f32_e32 v145, v145, v197
	v_sub_f32_e32 v146, v146, v197
	v_sub_f32_e32 v147, v147, v197
	v_sub_f32_e32 v148, v148, v197
	v_sub_f32_e32 v149, v149, v197
	v_sub_f32_e32 v150, v150, v197
	v_sub_f32_e32 v151, v151, v197
	v_sub_f32_e32 v152, v152, v197
	v_sub_f32_e32 v153, v153, v197
	v_sub_f32_e32 v154, v154, v197
	v_sub_f32_e32 v155, v155, v197
	v_sub_f32_e32 v156, v156, v197
	v_sub_f32_e32 v157, v157, v197
	v_sub_f32_e32 v158, v158, v197
	v_sub_f32_e32 v159, v159, v197
	v_sub_f32_e32 v198, v198, v197
	v_sub_f32_e32 v199, v199, v197
	v_sub_f32_e32 v200, v200, v197
	v_sub_f32_e32 v201, v201, v197
	v_sub_f32_e32 v202, v202, v197
	v_sub_f32_e32 v203, v203, v197
	v_sub_f32_e32 v204, v204, v197
	v_sub_f32_e32 v205, v205, v197
	v_sub_f32_e32 v206, v206, v197
	v_sub_f32_e32 v207, v207, v197
	v_sub_f32_e32 v208, v208, v197
	v_sub_f32_e32 v209, v209, v197
	v_sub_f32_e32 v210, v210, v197
	v_sub_f32_e32 v211, v211, v197
	v_sub_f32_e32 v212, v212, v197
	v_sub_f32_e32 v213, v213, v197
	v_cmp_gt_f32_e64 s[12:13], 1.0, v242
.Lmla_ok_B:
	s_waitcnt lgkmcnt(6)
	v_mfma_f32_32x32x16_bf16 v[32:47], v[68:71], v[88:91], v[32:47]
	ds_read_b64_tr_b16 v[222:223], v183 offset:9216
	ds_read_b64_tr_b16 v[224:225], v183 offset:9472
	v_exp_f32_e32 v128, v128
	v_exp_f32_e32 v129, v129
	v_exp_f32_e32 v130, v130
	s_waitcnt lgkmcnt(6)
	v_mfma_f32_32x32x16_bf16 v[16:31], v[68:71], v[92:95], v[16:31]
	ds_read_b64_tr_b16 v[226:227], v183 offset:9728
	ds_read_b64_tr_b16 v[228:229], v183 offset:9984
	v_exp_f32_e32 v131, v131
	v_exp_f32_e32 v132, v132
	v_exp_f32_e32 v133, v133
	s_waitcnt lgkmcnt(6)
	v_mfma_f32_32x32x16_bf16 v[0:15], v[80:83], v[214:217], v[0:15]
	ds_read_b64_tr_b16 v[72:73], v183 offset:12288
	ds_read_b64_tr_b16 v[74:75], v183 offset:12544
	v_exp_f32_e32 v134, v134
	v_exp_f32_e32 v135, v135
	v_exp_f32_e32 v136, v136
	s_waitcnt lgkmcnt(6)
	v_mfma_f32_32x32x16_bf16 v[48:63], v[80:83], v[218:221], v[48:63]
	ds_read_b64_tr_b16 v[76:77], v183 offset:12800
	ds_read_b64_tr_b16 v[78:79], v183 offset:13056
	v_exp_f32_e32 v137, v137
	v_exp_f32_e32 v138, v138
	v_exp_f32_e32 v139, v139
	s_waitcnt lgkmcnt(6)
	v_mfma_f32_32x32x16_bf16 v[32:47], v[80:83], v[222:225], v[32:47]
	ds_read_b64_tr_b16 v[88:89], v183 offset:13312
	ds_read_b64_tr_b16 v[90:91], v183 offset:13568
	v_exp_f32_e32 v140, v140
	v_exp_f32_e32 v141, v141
	v_exp_f32_e32 v142, v142
	s_waitcnt lgkmcnt(6)
	v_mfma_f32_32x32x16_bf16 v[16:31], v[80:83], v[226:229], v[16:31]
	ds_read_b64_tr_b16 v[92:93], v183 offset:13824
	ds_read_b64_tr_b16 v[94:95], v183 offset:14080
	v_exp_f32_e32 v143, v143
	s_waitcnt lgkmcnt(6)
	v_mfma_f32_32x32x16_bf16 v[0:15], v[84:87], v[72:75], v[0:15]
	s_waitcnt lgkmcnt(4)
	v_mfma_f32_32x32x16_bf16 v[48:63], v[84:87], v[76:79], v[48:63]
	s_waitcnt lgkmcnt(2)
	v_mfma_f32_32x32x16_bf16 v[32:47], v[84:87], v[88:91], v[32:47]
	s_waitcnt lgkmcnt(0)
	v_mfma_f32_32x32x16_bf16 v[16:31], v[84:87], v[92:95], v[16:31]
	s_cmp_lg_u64 s[12:13], 0
	s_cbranch_scc0 .Lmla_nors_B
	s_and_saveexec_b64 s[20:21], s[40:41]
	ds_write_b32 v162, v242 offset:128
	s_or_b64 exec, exec, s[20:21]
	s_waitcnt lgkmcnt(0)
	v_add_u32_e32 v245, s37, v184
	ds_read_b128 v[214:217], v245 offset:128
	ds_read_b128 v[218:221], v245 offset:160
	ds_read_b128 v[222:225], v245 offset:192
	ds_read_b128 v[226:229], v245 offset:224
	s_waitcnt lgkmcnt(0)
	v_pk_mul_f32 v[0:1], v[0:1], v[214:215]
	v_pk_mul_f32 v[2:3], v[2:3], v[216:217]
	v_pk_mul_f32 v[4:5], v[4:5], v[218:219]
	v_pk_mul_f32 v[6:7], v[6:7], v[220:221]
	v_pk_mul_f32 v[8:9], v[8:9], v[222:223]
	v_pk_mul_f32 v[10:11], v[10:11], v[224:225]
	v_pk_mul_f32 v[12:13], v[12:13], v[226:227]
	v_pk_mul_f32 v[14:15], v[14:15], v[228:229]
	v_pk_mul_f32 v[48:49], v[48:49], v[214:215]
	v_pk_mul_f32 v[50:51], v[50:51], v[216:217]
	v_pk_mul_f32 v[52:53], v[52:53], v[218:219]
	v_pk_mul_f32 v[54:55], v[54:55], v[220:221]
	v_pk_mul_f32 v[56:57], v[56:57], v[222:223]
	v_pk_mul_f32 v[58:59], v[58:59], v[224:225]
	v_pk_mul_f32 v[60:61], v[60:61], v[226:227]
	v_pk_mul_f32 v[62:63], v[62:63], v[228:229]
	v_pk_mul_f32 v[32:33], v[32:33], v[214:215]
	v_pk_mul_f32 v[34:35], v[34:35], v[216:217]
	v_pk_mul_f32 v[36:37], v[36:37], v[218:219]
	v_pk_mul_f32 v[38:39], v[38:39], v[220:221]
	v_pk_mul_f32 v[40:41], v[40:41], v[222:223]
	v_pk_mul_f32 v[42:43], v[42:43], v[224:225]
	v_pk_mul_f32 v[44:45], v[44:45], v[226:227]
	v_pk_mul_f32 v[46:47], v[46:47], v[228:229]
	v_pk_mul_f32 v[16:17], v[16:17], v[214:215]
	v_pk_mul_f32 v[18:19], v[18:19], v[216:217]
	v_pk_mul_f32 v[20:21], v[20:21], v[218:219]
	v_pk_mul_f32 v[22:23], v[22:23], v[220:221]
	v_pk_mul_f32 v[24:25], v[24:25], v[222:223]
	v_pk_mul_f32 v[26:27], v[26:27], v[224:225]
	v_pk_mul_f32 v[28:29], v[28:29], v[226:227]
	v_pk_mul_f32 v[30:31], v[30:31], v[228:229]
